# experiment: divided L2 touch-prefetch (6 K-tiles ahead) inside the FFN-up GEMM K-loop
# speedup vs baseline: 1.1059x; 1.1059x over previous
.LBB0_1134:
	v_readlane_b32 s100, v254, 27
	s_nop 3
	s_cmp_lt_u32 s100, 4
	s_cselect_b32 s98, s20, s22
	s_cselect_b32 s99, s21, s23
	s_cselect_b32 s101, s43, s18
	s_and_b32 s101, s101, 3
	s_lshl_b32 s101, s101, 6
	s_and_b32 s100, s100, 3
	s_lshl_b32 s100, s100, 4
	s_add_i32 s101, s101, s100
	v_and_b32_e32 v226, 15, v237
	v_add_u32_e32 v226, s101, v226
	v_lshlrev_b32_e32 v226, 12, v226
	s_add_u32 s98, s98, 0x300
	s_addc_u32 s99, s99, 0
	s_ashr_i32 s13, s12, 31
	s_lshl_b64 s[14:15], s[12:13], 20
	s_add_u32 s14, s26, s14
	s_addc_u32 s15, s27, s15
	s_and_b64 s[16:17], s[0:1], exec
	s_cselect_b32 s13, s15, s21
	s_cselect_b32 s44, s14, s20
	s_ashr_i32 s11, s10, 31
	s_lshl_b64 s[16:17], s[10:11], 20
	s_add_u32 s16, s28, s16
	s_addc_u32 s17, s29, s17
	s_and_b64 s[24:25], s[0:1], exec
	s_cselect_b32 s11, s17, s23
	s_cselect_b32 s45, s16, s22
	s_add_u32 s20, s20, 0x80080
	s_addc_u32 s21, s21, 0
	s_add_u32 s46, s22, 0x100
	v_mov_b32_e32 v2, 0
	s_addc_u32 s47, s23, 0
	s_mov_b32 s48, -2
	v_mov_b32_e32 v3, v2
	v_mov_b32_e32 v4, v2
	v_mov_b32_e32 v5, v2
	v_mov_b32_e32 v6, v2
	v_mov_b32_e32 v7, v2
	v_mov_b32_e32 v8, v2
	v_mov_b32_e32 v9, v2
	v_mov_b32_e32 v18, v2
	v_mov_b32_e32 v19, v2
	v_mov_b32_e32 v20, v2
	v_mov_b32_e32 v21, v2
	v_mov_b32_e32 v22, v2
	v_mov_b32_e32 v23, v2
	v_mov_b32_e32 v24, v2
	v_mov_b32_e32 v25, v2
	v_mov_b32_e32 v34, v2
	v_mov_b32_e32 v35, v2
	v_mov_b32_e32 v36, v2
	v_mov_b32_e32 v37, v2
	v_mov_b32_e32 v38, v2
	v_mov_b32_e32 v39, v2
	v_mov_b32_e32 v40, v2
	v_mov_b32_e32 v41, v2
	v_mov_b32_e32 v50, v2
	v_mov_b32_e32 v51, v2
	v_mov_b32_e32 v52, v2
	v_mov_b32_e32 v53, v2
	v_mov_b32_e32 v54, v2
	v_mov_b32_e32 v55, v2
	v_mov_b32_e32 v56, v2
	v_mov_b32_e32 v57, v2
	v_mov_b32_e32 v10, v2
	v_mov_b32_e32 v11, v2
	v_mov_b32_e32 v12, v2
	v_mov_b32_e32 v13, v2
	v_mov_b32_e32 v14, v2
	v_mov_b32_e32 v15, v2
	v_mov_b32_e32 v16, v2
	v_mov_b32_e32 v17, v2
	v_mov_b32_e32 v26, v2
	s_waitcnt lgkmcnt(0)
	v_mov_b32_e32 v27, v2
	v_mov_b32_e32 v28, v2
	v_mov_b32_e32 v29, v2
	v_mov_b32_e32 v30, v2
	v_mov_b32_e32 v31, v2
	v_mov_b32_e32 v32, v2
	v_mov_b32_e32 v33, v2
	v_mov_b32_e32 v42, v2
	v_mov_b32_e32 v43, v2
	v_mov_b32_e32 v44, v2
	v_mov_b32_e32 v45, v2
	v_mov_b32_e32 v46, v2
	v_mov_b32_e32 v47, v2
	v_mov_b32_e32 v48, v2
	v_mov_b32_e32 v49, v2
	v_mov_b32_e32 v58, v2
	v_mov_b32_e32 v59, v2
	v_mov_b32_e32 v60, v2
	v_mov_b32_e32 v61, v2
	v_mov_b32_e32 v62, v2
	v_mov_b32_e32 v63, v2
	v_mov_b32_e32 v64, v2
	v_mov_b32_e32 v65, v2
	v_mov_b32_e32 v66, v2
	v_mov_b32_e32 v67, v2
	v_mov_b32_e32 v68, v2
	v_mov_b32_e32 v69, v2
	v_mov_b32_e32 v70, v2
	v_mov_b32_e32 v71, v2
	v_mov_b32_e32 v72, v2
	v_mov_b32_e32 v73, v2
	v_mov_b32_e32 v82, v2
	v_mov_b32_e32 v83, v2
	v_mov_b32_e32 v84, v2
	v_mov_b32_e32 v85, v2
	v_mov_b32_e32 v86, v2
	v_mov_b32_e32 v87, v2
	v_mov_b32_e32 v88, v2
	v_mov_b32_e32 v89, v2
	v_mov_b32_e32 v98, v2
	v_mov_b32_e32 v99, v2
	v_mov_b32_e32 v100, v2
	v_mov_b32_e32 v101, v2
	v_mov_b32_e32 v102, v2
	v_mov_b32_e32 v103, v2
	v_mov_b32_e32 v104, v2
	v_mov_b32_e32 v105, v2
	v_mov_b32_e32 v114, v2
	v_mov_b32_e32 v115, v2
	v_mov_b32_e32 v116, v2
	v_mov_b32_e32 v117, v2
	v_mov_b32_e32 v118, v2
	v_mov_b32_e32 v119, v2
	v_mov_b32_e32 v120, v2
	v_mov_b32_e32 v121, v2
	v_mov_b32_e32 v74, v2
	v_mov_b32_e32 v75, v2
	v_mov_b32_e32 v76, v2
	v_mov_b32_e32 v77, v2
	v_mov_b32_e32 v78, v2
	v_mov_b32_e32 v79, v2
	v_mov_b32_e32 v80, v2
	v_mov_b32_e32 v81, v2
	v_mov_b32_e32 v90, v2
	v_mov_b32_e32 v91, v2
	v_mov_b32_e32 v92, v2
	v_mov_b32_e32 v93, v2
	v_mov_b32_e32 v94, v2
	v_mov_b32_e32 v95, v2
	v_mov_b32_e32 v96, v2
	v_mov_b32_e32 v97, v2
	v_mov_b32_e32 v106, v2
	v_mov_b32_e32 v107, v2
	v_mov_b32_e32 v108, v2
	v_mov_b32_e32 v109, v2
	v_mov_b32_e32 v110, v2
	v_mov_b32_e32 v111, v2
	v_mov_b32_e32 v112, v2
	v_mov_b32_e32 v113, v2
	v_mov_b32_e32 v122, v2
	v_mov_b32_e32 v123, v2
	v_mov_b32_e32 v124, v2
	v_mov_b32_e32 v125, v2
	v_mov_b32_e32 v126, v2
	v_mov_b32_e32 v127, v2
	v_mov_b32_e32 v128, v2
	v_mov_b32_e32 v129, v2
.LBB0_1135:
	ds_read_b128 v[152:155], v149
	ds_read_b128 v[156:159], v149 offset:1024
	ds_read_b128 v[160:163], v149 offset:2048
	ds_read_b128 v[164:167], v149 offset:3072
	ds_read_b128 v[168:171], v150
	ds_read_b128 v[172:175], v150 offset:1024
	ds_read_b128 v[176:179], v150 offset:2048
	ds_read_b128 v[180:183], v150 offset:3072
	s_add_u32 s22, s20, 0xfff80080
	s_addc_u32 s23, s21, -1
	s_cmp_eq_u32 s48, 28
	s_cselect_b32 s25, s13, s23
	s_cselect_b32 s24, s44, s22
	s_cselect_b32 s23, s11, s47
	s_cselect_b32 s22, s45, s46
	v_lshl_add_u64 v[216:217], s[20:21], 0, v[138:139]
	s_add_i32 m0, s19, 0xc000
	ds_read_b128 v[184:187], v151
	ds_read_b128 v[188:191], v151 offset:1024
	ds_read_b128 v[192:195], v151 offset:2048
	ds_read_b128 v[196:199], v151 offset:3072
	ds_read_b128 v[200:203], v151 offset:4096
	ds_read_b128 v[204:207], v151 offset:5120
	ds_read_b128 v[208:211], v151 offset:6144
	ds_read_b128 v[212:215], v151 offset:7168
	global_load_lds_dwordx4 v[216:217], off
	v_lshl_add_u64 v[216:217], s[20:21], 0, v[140:141]
	s_add_i32 m0, s19, 0xe000
	s_nop 0
	global_load_lds_dwordx4 v[216:217], off
	global_load_dword v227, v226, s[98:99]
	s_waitcnt vmcnt(9)
	s_waitcnt lgkmcnt(0)
	s_barrier
	s_setprio 1
	s_waitcnt lgkmcnt(0)
	v_mfma_f32_16x16x32_bf16 v[126:129], v[152:155], v[184:187], v[126:129]
	v_mfma_f32_16x16x32_bf16 v[122:125], v[160:163], v[184:187], v[122:125]
	v_mfma_f32_16x16x32_bf16 v[110:113], v[152:155], v[192:195], v[110:113]
	v_mfma_f32_16x16x32_bf16 v[106:109], v[160:163], v[192:195], v[106:109]
	v_mfma_f32_16x16x32_bf16 v[94:97], v[152:155], v[200:203], v[94:97]
	v_mfma_f32_16x16x32_bf16 v[90:93], v[160:163], v[200:203], v[90:93]
	v_mfma_f32_16x16x32_bf16 v[78:81], v[152:155], v[208:211], v[78:81]
	v_mfma_f32_16x16x32_bf16 v[74:77], v[160:163], v[208:211], v[74:77]
	v_mfma_f32_16x16x32_bf16 v[126:129], v[156:159], v[188:191], v[126:129]
	v_mfma_f32_16x16x32_bf16 v[122:125], v[164:167], v[188:191], v[122:125]
	v_mfma_f32_16x16x32_bf16 v[110:113], v[156:159], v[196:199], v[110:113]
	v_mfma_f32_16x16x32_bf16 v[106:109], v[164:167], v[196:199], v[106:109]
	v_mfma_f32_16x16x32_bf16 v[94:97], v[156:159], v[204:207], v[94:97]
	v_mfma_f32_16x16x32_bf16 v[90:93], v[164:167], v[204:207], v[90:93]
	v_mfma_f32_16x16x32_bf16 v[78:81], v[156:159], v[212:215], v[78:81]
	v_mfma_f32_16x16x32_bf16 v[74:77], v[164:167], v[212:215], v[74:77]
	s_setprio 0
	s_setprio 1
	v_mfma_f32_16x16x32_bf16 v[118:121], v[168:171], v[184:187], v[118:121]
	v_mfma_f32_16x16x32_bf16 v[114:117], v[176:179], v[184:187], v[114:117]
	v_mfma_f32_16x16x32_bf16 v[102:105], v[168:171], v[192:195], v[102:105]
	v_mfma_f32_16x16x32_bf16 v[98:101], v[176:179], v[192:195], v[98:101]
	v_mfma_f32_16x16x32_bf16 v[86:89], v[168:171], v[200:203], v[86:89]
	v_mfma_f32_16x16x32_bf16 v[82:85], v[176:179], v[200:203], v[82:85]
	v_mfma_f32_16x16x32_bf16 v[70:73], v[168:171], v[208:211], v[70:73]
	v_mfma_f32_16x16x32_bf16 v[66:69], v[176:179], v[208:211], v[66:69]
	v_mfma_f32_16x16x32_bf16 v[118:121], v[172:175], v[188:191], v[118:121]
	v_mfma_f32_16x16x32_bf16 v[114:117], v[180:183], v[188:191], v[114:117]
	v_mfma_f32_16x16x32_bf16 v[102:105], v[172:175], v[196:199], v[102:105]
	v_mfma_f32_16x16x32_bf16 v[98:101], v[180:183], v[196:199], v[98:101]
	v_mfma_f32_16x16x32_bf16 v[86:89], v[172:175], v[204:207], v[86:89]
	v_mfma_f32_16x16x32_bf16 v[82:85], v[180:183], v[204:207], v[82:85]
	v_mfma_f32_16x16x32_bf16 v[70:73], v[172:175], v[212:215], v[70:73]
	v_mfma_f32_16x16x32_bf16 v[66:69], v[180:183], v[212:215], v[66:69]
	s_setprio 0
	s_barrier
	s_add_i32 s49, s40, s30
	v_lshl_add_u64 v[216:217], s[22:23], 0, v[132:133]
	s_mov_b32 m0, s49
	ds_read_b128 v[184:187], v151 offset:16384
	ds_read_b128 v[188:191], v151 offset:17408
	ds_read_b128 v[192:195], v151 offset:18432
	ds_read_b128 v[196:199], v151 offset:19456
	ds_read_b128 v[200:203], v151 offset:20480
	ds_read_b128 v[204:207], v151 offset:21504
	ds_read_b128 v[208:211], v151 offset:22528
	ds_read_b128 v[212:215], v151 offset:23552
	global_load_lds_dwordx4 v[216:217], off
	s_add_i32 m0, s49, 0x2000
	s_add_u32 s50, s22, 0x80000
	v_lshl_add_u64 v[218:219], s[22:23], 0, v[136:137]
	s_addc_u32 s51, s23, 0
	s_add_i32 s49, s41, s30
	global_load_lds_dwordx4 v[218:219], off
	v_lshl_add_u64 v[220:221], s[50:51], 0, v[132:133]
	s_mov_b32 m0, s49
	v_lshl_add_u64 v[222:223], s[24:25], 0, v[134:135]
	global_load_lds_dwordx4 v[220:221], off
	v_lshl_add_u64 v[220:221], s[50:51], 0, v[136:137]
	s_add_i32 m0, s49, 0x2000
	s_nop 0
	global_load_lds_dwordx4 v[220:221], off
	v_lshl_add_u64 v[220:221], s[24:25], 0, v[130:131]
	s_mov_b32 m0, s19
	s_nop 0
	global_load_lds_dwordx4 v[220:221], off
	s_mov_b32 m0, s33
	s_nop 0
	global_load_lds_dwordx4 v[222:223], off
	s_waitcnt vmcnt(9)
	s_waitcnt lgkmcnt(0)
	s_barrier
	s_setprio 1
	s_waitcnt lgkmcnt(0)
	v_mfma_f32_16x16x32_bf16 v[62:65], v[152:155], v[184:187], v[62:65]
	v_mfma_f32_16x16x32_bf16 v[58:61], v[160:163], v[184:187], v[58:61]
	v_mfma_f32_16x16x32_bf16 v[46:49], v[152:155], v[192:195], v[46:49]
	v_mfma_f32_16x16x32_bf16 v[42:45], v[160:163], v[192:195], v[42:45]
	v_mfma_f32_16x16x32_bf16 v[30:33], v[152:155], v[200:203], v[30:33]
	v_mfma_f32_16x16x32_bf16 v[26:29], v[160:163], v[200:203], v[26:29]
	v_mfma_f32_16x16x32_bf16 v[14:17], v[152:155], v[208:211], v[14:17]
	v_mfma_f32_16x16x32_bf16 v[10:13], v[160:163], v[208:211], v[10:13]
	v_mfma_f32_16x16x32_bf16 v[62:65], v[156:159], v[188:191], v[62:65]
	v_mfma_f32_16x16x32_bf16 v[58:61], v[164:167], v[188:191], v[58:61]
	v_mfma_f32_16x16x32_bf16 v[46:49], v[156:159], v[196:199], v[46:49]
	v_mfma_f32_16x16x32_bf16 v[42:45], v[164:167], v[196:199], v[42:45]
	v_mfma_f32_16x16x32_bf16 v[30:33], v[156:159], v[204:207], v[30:33]
	v_mfma_f32_16x16x32_bf16 v[26:29], v[164:167], v[204:207], v[26:29]
	v_mfma_f32_16x16x32_bf16 v[14:17], v[156:159], v[212:215], v[14:17]
	v_mfma_f32_16x16x32_bf16 v[10:13], v[164:167], v[212:215], v[10:13]
	s_setprio 0
	s_setprio 1
	v_mfma_f32_16x16x32_bf16 v[54:57], v[168:171], v[184:187], v[54:57]
	v_mfma_f32_16x16x32_bf16 v[50:53], v[176:179], v[184:187], v[50:53]
	v_mfma_f32_16x16x32_bf16 v[38:41], v[168:171], v[192:195], v[38:41]
	v_mfma_f32_16x16x32_bf16 v[34:37], v[176:179], v[192:195], v[34:37]
	v_mfma_f32_16x16x32_bf16 v[22:25], v[168:171], v[200:203], v[22:25]
	v_mfma_f32_16x16x32_bf16 v[18:21], v[176:179], v[200:203], v[18:21]
	v_mfma_f32_16x16x32_bf16 v[6:9], v[168:171], v[208:211], v[6:9]
	v_mfma_f32_16x16x32_bf16 v[2:5], v[176:179], v[208:211], v[2:5]
	v_mfma_f32_16x16x32_bf16 v[54:57], v[172:175], v[188:191], v[54:57]
	v_mfma_f32_16x16x32_bf16 v[50:53], v[180:183], v[188:191], v[50:53]
	v_mfma_f32_16x16x32_bf16 v[38:41], v[172:175], v[196:199], v[38:41]
	v_mfma_f32_16x16x32_bf16 v[34:37], v[180:183], v[196:199], v[34:37]
	v_mfma_f32_16x16x32_bf16 v[22:25], v[172:175], v[204:207], v[22:25]
	v_mfma_f32_16x16x32_bf16 v[18:21], v[180:183], v[204:207], v[18:21]
	v_mfma_f32_16x16x32_bf16 v[6:9], v[172:175], v[212:215], v[6:9]
	v_mfma_f32_16x16x32_bf16 v[2:5], v[180:183], v[212:215], v[2:5]
	s_setprio 0
	s_barrier
	s_add_i32 s49, 0, 0x18000
	s_add_i32 s50, 0, 0x1c000
	v_add_u32_e32 v164, s49, v147
	v_add_u32_e32 v180, s50, v147
	ds_read_b128 v[152:155], v164
	ds_read_b128 v[156:159], v164 offset:1024
	ds_read_b128 v[160:163], v164 offset:2048
	ds_read_b128 v[164:167], v164 offset:3072
	ds_read_b128 v[168:171], v180
	ds_read_b128 v[172:175], v180 offset:1024
	ds_read_b128 v[176:179], v180 offset:2048
	ds_read_b128 v[180:183], v180 offset:3072
	s_add_u32 s24, s24, 0x80000
	s_addc_u32 s25, s25, 0
	s_mov_b32 m0, s34
	v_lshl_add_u64 v[224:225], s[24:25], 0, v[130:131]
	ds_read_b128 v[184:187], v151 offset:32768
	ds_read_b128 v[188:191], v151 offset:33792
	ds_read_b128 v[192:195], v151 offset:34816
	ds_read_b128 v[196:199], v151 offset:35840
	ds_read_b128 v[200:203], v151 offset:36864
	ds_read_b128 v[204:207], v151 offset:37888
	ds_read_b128 v[208:211], v151 offset:38912
	ds_read_b128 v[212:215], v151 offset:39936
	global_load_lds_dwordx4 v[224:225], off
	v_lshl_add_u64 v[224:225], s[24:25], 0, v[134:135]
	s_mov_b32 m0, s35
	s_nop 0
	global_load_lds_dwordx4 v[224:225], off
	global_load_dword v227, v226, s[98:99] offset:128
	s_add_u32 s98, s98, 0x100
	s_addc_u32 s99, s99, 0
	s_waitcnt vmcnt(9)
	s_waitcnt lgkmcnt(0)
	s_barrier
	s_setprio 1
	s_waitcnt lgkmcnt(0)
	v_mfma_f32_16x16x32_bf16 v[126:129], v[152:155], v[184:187], v[126:129]
	v_mfma_f32_16x16x32_bf16 v[122:125], v[160:163], v[184:187], v[122:125]
	v_mfma_f32_16x16x32_bf16 v[110:113], v[152:155], v[192:195], v[110:113]
	v_mfma_f32_16x16x32_bf16 v[106:109], v[160:163], v[192:195], v[106:109]
	v_mfma_f32_16x16x32_bf16 v[94:97], v[152:155], v[200:203], v[94:97]
	v_mfma_f32_16x16x32_bf16 v[90:93], v[160:163], v[200:203], v[90:93]
	v_mfma_f32_16x16x32_bf16 v[78:81], v[152:155], v[208:211], v[78:81]
	v_mfma_f32_16x16x32_bf16 v[74:77], v[160:163], v[208:211], v[74:77]
	v_mfma_f32_16x16x32_bf16 v[126:129], v[156:159], v[188:191], v[126:129]
	v_mfma_f32_16x16x32_bf16 v[122:125], v[164:167], v[188:191], v[122:125]
	v_mfma_f32_16x16x32_bf16 v[110:113], v[156:159], v[196:199], v[110:113]
	v_mfma_f32_16x16x32_bf16 v[106:109], v[164:167], v[196:199], v[106:109]
	v_mfma_f32_16x16x32_bf16 v[94:97], v[156:159], v[204:207], v[94:97]
	v_mfma_f32_16x16x32_bf16 v[90:93], v[164:167], v[204:207], v[90:93]
	v_mfma_f32_16x16x32_bf16 v[78:81], v[156:159], v[212:215], v[78:81]
	v_mfma_f32_16x16x32_bf16 v[74:77], v[164:167], v[212:215], v[74:77]
	s_setprio 0
	s_setprio 1
	v_mfma_f32_16x16x32_bf16 v[118:121], v[168:171], v[184:187], v[118:121]
	v_mfma_f32_16x16x32_bf16 v[114:117], v[176:179], v[184:187], v[114:117]
	v_mfma_f32_16x16x32_bf16 v[102:105], v[168:171], v[192:195], v[102:105]
	v_mfma_f32_16x16x32_bf16 v[98:101], v[176:179], v[192:195], v[98:101]
	v_mfma_f32_16x16x32_bf16 v[86:89], v[168:171], v[200:203], v[86:89]
	v_mfma_f32_16x16x32_bf16 v[82:85], v[176:179], v[200:203], v[82:85]
	v_mfma_f32_16x16x32_bf16 v[70:73], v[168:171], v[208:211], v[70:73]
	v_mfma_f32_16x16x32_bf16 v[66:69], v[176:179], v[208:211], v[66:69]
	v_mfma_f32_16x16x32_bf16 v[118:121], v[172:175], v[188:191], v[118:121]
	v_mfma_f32_16x16x32_bf16 v[114:117], v[180:183], v[188:191], v[114:117]
	v_mfma_f32_16x16x32_bf16 v[102:105], v[172:175], v[196:199], v[102:105]
	v_mfma_f32_16x16x32_bf16 v[98:101], v[180:183], v[196:199], v[98:101]
	v_mfma_f32_16x16x32_bf16 v[86:89], v[172:175], v[204:207], v[86:89]
	v_mfma_f32_16x16x32_bf16 v[82:85], v[180:183], v[204:207], v[82:85]
	v_mfma_f32_16x16x32_bf16 v[70:73], v[172:175], v[212:215], v[70:73]
	v_mfma_f32_16x16x32_bf16 v[66:69], v[180:183], v[212:215], v[66:69]
	s_setprio 0
	s_barrier
	s_add_i32 s24, s49, s30
	v_lshl_add_u64 v[216:217], v[216:217], 0, s[6:7]
	s_mov_b32 m0, s24
	ds_read_b128 v[184:187], v151 offset:49152
	ds_read_b128 v[188:191], v151 offset:50176
	ds_read_b128 v[192:195], v151 offset:51200
	ds_read_b128 v[196:199], v151 offset:52224
	ds_read_b128 v[200:203], v151 offset:53248
	ds_read_b128 v[204:207], v151 offset:54272
	ds_read_b128 v[208:211], v151 offset:55296
	ds_read_b128 v[212:215], v151 offset:56320
	global_load_lds_dwordx4 v[216:217], off
	s_add_i32 m0, s24, 0x2000
	s_add_u32 s22, s22, 0x80080
	v_lshl_add_u64 v[216:217], v[218:219], 0, s[6:7]
	s_addc_u32 s23, s23, 0
	s_add_i32 s24, s50, s30
	global_load_lds_dwordx4 v[216:217], off
	v_lshl_add_u64 v[216:217], s[22:23], 0, v[132:133]
	s_mov_b32 m0, s24
	s_nop 0
	global_load_lds_dwordx4 v[216:217], off
	v_lshl_add_u64 v[216:217], s[22:23], 0, v[136:137]
	s_add_i32 m0, s24, 0x2000
	s_nop 0
	global_load_lds_dwordx4 v[216:217], off
	v_lshl_add_u64 v[216:217], v[220:221], 0, s[6:7]
	s_mov_b32 m0, s38
	s_nop 0
	global_load_lds_dwordx4 v[216:217], off
	v_lshl_add_u64 v[216:217], v[222:223], 0, s[6:7]
	s_mov_b32 m0, s39
	s_nop 0
	global_load_lds_dwordx4 v[216:217], off
	s_waitcnt vmcnt(9)
	s_waitcnt lgkmcnt(0)
	s_barrier
	s_setprio 1
	s_waitcnt lgkmcnt(0)
	v_mfma_f32_16x16x32_bf16 v[62:65], v[152:155], v[184:187], v[62:65]
	v_mfma_f32_16x16x32_bf16 v[58:61], v[160:163], v[184:187], v[58:61]
	v_mfma_f32_16x16x32_bf16 v[46:49], v[152:155], v[192:195], v[46:49]
	v_mfma_f32_16x16x32_bf16 v[42:45], v[160:163], v[192:195], v[42:45]
	v_mfma_f32_16x16x32_bf16 v[30:33], v[152:155], v[200:203], v[30:33]
	v_mfma_f32_16x16x32_bf16 v[26:29], v[160:163], v[200:203], v[26:29]
	v_mfma_f32_16x16x32_bf16 v[14:17], v[152:155], v[208:211], v[14:17]
	v_mfma_f32_16x16x32_bf16 v[10:13], v[160:163], v[208:211], v[10:13]
	v_mfma_f32_16x16x32_bf16 v[62:65], v[156:159], v[188:191], v[62:65]
	v_mfma_f32_16x16x32_bf16 v[58:61], v[164:167], v[188:191], v[58:61]
	v_mfma_f32_16x16x32_bf16 v[46:49], v[156:159], v[196:199], v[46:49]
	v_mfma_f32_16x16x32_bf16 v[42:45], v[164:167], v[196:199], v[42:45]
	v_mfma_f32_16x16x32_bf16 v[30:33], v[156:159], v[204:207], v[30:33]
	v_mfma_f32_16x16x32_bf16 v[26:29], v[164:167], v[204:207], v[26:29]
	v_mfma_f32_16x16x32_bf16 v[14:17], v[156:159], v[212:215], v[14:17]
	v_mfma_f32_16x16x32_bf16 v[10:13], v[164:167], v[212:215], v[10:13]
	s_setprio 0
	s_setprio 1
	v_mfma_f32_16x16x32_bf16 v[54:57], v[168:171], v[184:187], v[54:57]
	v_mfma_f32_16x16x32_bf16 v[50:53], v[176:179], v[184:187], v[50:53]
	v_mfma_f32_16x16x32_bf16 v[38:41], v[168:171], v[192:195], v[38:41]
	v_mfma_f32_16x16x32_bf16 v[34:37], v[176:179], v[192:195], v[34:37]
	v_mfma_f32_16x16x32_bf16 v[22:25], v[168:171], v[200:203], v[22:25]
	v_mfma_f32_16x16x32_bf16 v[18:21], v[176:179], v[200:203], v[18:21]
	v_mfma_f32_16x16x32_bf16 v[6:9], v[168:171], v[208:211], v[6:9]
	v_mfma_f32_16x16x32_bf16 v[2:5], v[176:179], v[208:211], v[2:5]
	v_mfma_f32_16x16x32_bf16 v[54:57], v[172:175], v[188:191], v[54:57]
	v_mfma_f32_16x16x32_bf16 v[50:53], v[180:183], v[188:191], v[50:53]
	v_mfma_f32_16x16x32_bf16 v[38:41], v[172:175], v[196:199], v[38:41]
	v_mfma_f32_16x16x32_bf16 v[34:37], v[180:183], v[196:199], v[34:37]
	v_mfma_f32_16x16x32_bf16 v[22:25], v[172:175], v[204:207], v[22:25]
	v_mfma_f32_16x16x32_bf16 v[18:21], v[180:183], v[204:207], v[18:21]
	v_mfma_f32_16x16x32_bf16 v[6:9], v[172:175], v[212:215], v[6:9]
	v_mfma_f32_16x16x32_bf16 v[2:5], v[180:183], v[212:215], v[2:5]
	s_setprio 0
	s_barrier
	s_add_i32 s48, s48, 2
	s_add_u32 s20, s20, 0x100
	s_addc_u32 s21, s21, 0
	s_add_u32 s46, s46, 0x100
	s_addc_u32 s47, s47, 0
	s_cmp_gt_u32 s48, 29
	s_cbranch_scc0 .LBB0_1135
	v_readlane_b32 s44, v254, 52
	s_and_b64 vcc, exec, s[8:9]
	v_readlane_b32 s45, v254, 53
	v_readlane_b32 s46, v254, 54
	v_readlane_b32 s47, v254, 55
	s_cbranch_vccz .LBB0_1138
	s_barrier
